# step 0 keeps only LDS waits (Q fragments are waited for earlier on both paths), so the V0 DMA of a prefetched unit is not drained mid-step
# baseline (speedup 1.0000x reference)
;   #define CINIT(C0,C1,btl) do{ const float b_=(btl); _Pragma("unroll") for(int r=0;r<16;++r){ C0[r]=__builtin_fmaf(s2,(float)((r&3)+8*(r>>2)),b_); C1[r]=__builtin_fmaf(s2,(float)((r&3)+8*(r>>2)+32),b_);} }while(0)
;   #define CMASK(P0,P1,t) do{ if(WIN||(t)>=NT-4)gmask(P0,P1,64*(t),qrel,hi,WIN);}while(0)
;   #define START(P0,P1) do{ resc=false; \
;     if(!NOMAX){ const float rm=rowmax(P0,P1); const float dl=__builtin_fmaxf(rm,0.f);     \
;       mhat=fadd_s(mhat,dl); \
;       _Pragma("unroll") for(int r=0;r<16;++r){P0[r]=fsub_s(P0[r],dl);P1[r]=fsub_s(P1[r],dl);} } \
;     _Pragma("unroll") for(int r=0;r<16;++r)P0[r]=__builtin_amdgcn_exp2f(P0[r]); }while(0)
;   #define CMASK(P0,P1,t) do{}while(0)
;   #define CMASK(P0,P1,t) do{ if(WIN||(t)>=NT-4)gmask(P0,P1,64*(t),qrel,hi,WIN);}while(0)
; __device__ __forceinline__ void qkt(f32x16&p0,f32x16&p1,const char*Kslot,const bf16x8*qr,int r32,int hi){
;   const char*kb=Kslot+hi*1024+r32*16;
;   #pragma unroll
;   for(int d0=0;d0<4;++d0){
;     const bf16x8 b0=*reinterpret_cast<const bf16x8*>(kb+d0*2048);
;     const bf16x8 b1=*reinterpret_cast<const bf16x8*>(kb+d0*2048+512);
;     p0=__builtin_amdgcn_mfma_f32_32x32x16_bf16(b0,qr[d0],p0,0,0,0);p1=__builtin_amdgcn_mfma_f32_32x32x16_bf16(b1,qr[d0],p1,0,0,0);}
; }
; template<int THRL> __device__ __forceinline__ void attn_unit(long rowbase,int qb,int t0,bool WIN,bool NOMAX,const bf16*Qc,const bf16*__restrict__ Kc,const bf16*__restrict__ Vc,bf16*Oc,float s2,float sink2,char*shm,
;     bf16x8 (&qr)[4],bool pref,const bf16*qkvb,int vn,int in_){
;     ...
;   CINIT(pA0,pA1,-qb2); qkt(pA0,pA1,Kbase,qr,r32,hi);asm volatile("s_nop 15\n\ts_nop 7":"+v"(pA0),"+v"(pA1));CMASK(pA0,pA1,0);
;   START(pA0,pA1);
.LBB0_265:
	s_sub_i32 s38, s4, s45
	v_or_b32_e32 v18, s38, v180
	v_lshlrev_b32_e32 v230, 2, v181
	v_add_u32_e32 v223, s2, v18
	v_sub_u32_e32 v18, v223, v230
	v_cvt_f32_i32_e32 v19, v18
	v_lshlrev_b32_e32 v18, 10, v181
	v_lshlrev_b32_e32 v20, 4, v180
	v_add3_u32 v231, 0, v18, v20
	v_mul_f32_e32 v184, 0x3fb8aa3b, v34
	ds_read_b128 v[34:37], v231
	ds_read_b128 v[52:55], v231 offset:512
	v_mul_f32_e64 v186, v184, -v19
	v_fma_f32 v18, 0, v184, v186
	v_fma_f32 v19, v184, -v19, v184
	v_pk_fma_f32 v[20:21], v[184:185], s[8:9], v[186:187] op_sel_hi:[0,1,0]
	v_pk_fma_f32 v[22:23], v[184:185], s[10:11], v[186:187] op_sel_hi:[0,1,0]
	v_pk_fma_f32 v[24:25], v[184:185], s[12:13], v[186:187] op_sel_hi:[0,1,0]
	v_pk_fma_f32 v[26:27], v[184:185], s[14:15], v[186:187] op_sel_hi:[0,1,0]
	v_pk_fma_f32 v[28:29], v[184:185], s[16:17], v[186:187] op_sel_hi:[0,1,0]
	v_pk_fma_f32 v[30:31], v[184:185], s[18:19], v[186:187] op_sel_hi:[0,1,0]
	v_pk_fma_f32 v[32:33], v[184:185], s[20:21], v[186:187] op_sel_hi:[0,1,0]
	v_pk_fma_f32 v[48:49], v[184:185], s[22:23], v[186:187] op_sel_hi:[0,1,0]
	v_pk_fma_f32 v[46:47], v[184:185], s[24:25], v[186:187] op_sel_hi:[0,1,0]
	s_waitcnt lgkmcnt(1)
	v_mfma_f32_32x32x16_bf16 v[18:33], v[34:37], v[2:5], v[18:33]
	v_fma_f32 v44, v184, s26, v186
	v_fma_f32 v45, v184, s27, v186
	v_fma_f32 v42, v184, s28, v186
	v_fma_f32 v43, v184, s29, v186
	v_fma_f32 v40, v184, s30, v186
	v_fma_f32 v41, v184, s31, v186
	v_pk_fma_f32 v[38:39], v[184:185], s[34:35], v[186:187] op_sel_hi:[0,1,0]
	v_pk_fma_f32 v[36:37], v[184:185], s[36:37], v[186:187] op_sel_hi:[0,1,0]
	v_pk_fma_f32 v[34:35], v[184:185], s[92:93], v[186:187] op_sel_hi:[0,1,0]
	s_addk_i32 s4, 0x100
	s_lshr_b32 s4, s4, 6
	s_waitcnt lgkmcnt(0)
	v_mfma_f32_32x32x16_bf16 v[34:49], v[52:55], v[2:5], v[34:49]
	ds_read_b128 v[52:55], v231 offset:2048
	s_sub_i32 s4, s4, s48
	s_cmp_lg_u32 s62, 0
	s_cselect_b32 s4, 4, s4
	s_cmp_lt_i32 s4, 5
	s_cselect_b64 s[38:39], -1, 0
	s_or_b64 s[38:39], s[62:63], s[38:39]
	s_andn2_b64 vcc, exec, s[38:39]
	v_add_u32_e32 v224, 0xffffff80, v223
	s_waitcnt lgkmcnt(0)
	v_mfma_f32_32x32x16_bf16 v[18:33], v[52:55], v[6:9], v[18:33]
	ds_read_b128 v[52:55], v231 offset:2560
	s_waitcnt lgkmcnt(0)
	v_mfma_f32_32x32x16_bf16 v[34:49], v[52:55], v[6:9], v[34:49]
	ds_read_b128 v[52:55], v231 offset:4096
	s_waitcnt lgkmcnt(0)
	v_mfma_f32_32x32x16_bf16 v[18:33], v[52:55], v[10:13], v[18:33]
	ds_read_b128 v[52:55], v231 offset:4608
	s_waitcnt lgkmcnt(0)
	v_mfma_f32_32x32x16_bf16 v[34:49], v[52:55], v[10:13], v[34:49]
	ds_read_b128 v[52:55], v231 offset:6144
	s_waitcnt lgkmcnt(0)
	v_mfma_f32_32x32x16_bf16 v[18:33], v[52:55], v[14:17], v[18:33]
	ds_read_b128 v[52:55], v231 offset:6656
	s_waitcnt lgkmcnt(0)
	v_mfma_f32_32x32x16_bf16 v[34:49], v[52:55], v[14:17], v[34:49]
	v_cndmask_b32_e64 v52, 0, 1, s[62:63]
	v_cmp_ne_u32_e64 s[38:39], 1, v52
	s_nop 15
	s_nop 7
	s_cbranch_vccnz .LBB0_330
	v_sub_u32_e32 v52, v223, v230
	s_nop 0
	v_readfirstlane_b32 s40, v52
	s_cmp_gt_i32 s40, 66
	s_cbranch_scc1 .Lmy_mk_c_s0
	v_cmp_le_i32_e32 vcc, 0, v52
	v_cndmask_b32_e32 v18, v217, v18, vcc
	v_cmp_le_i32_e32 vcc, 32, v52
	v_cndmask_b32_e32 v34, v217, v34, vcc
	v_cmp_le_i32_e32 vcc, 1, v52
	v_cndmask_b32_e32 v19, v217, v19, vcc
	v_cmp_le_i32_e32 vcc, 33, v52
	v_cndmask_b32_e32 v35, v217, v35, vcc
	v_cmp_le_i32_e32 vcc, 2, v52
	v_cndmask_b32_e32 v20, v217, v20, vcc
	v_cmp_le_i32_e32 vcc, 34, v52
	v_cndmask_b32_e32 v36, v217, v36, vcc
	v_cmp_le_i32_e32 vcc, 3, v52
	v_cndmask_b32_e32 v21, v217, v21, vcc
	v_cmp_le_i32_e32 vcc, 35, v52
	v_cndmask_b32_e32 v37, v217, v37, vcc
	v_cmp_le_i32_e32 vcc, 8, v52
	v_cndmask_b32_e32 v22, v217, v22, vcc
	v_cmp_le_i32_e32 vcc, 40, v52
	v_cndmask_b32_e32 v38, v217, v38, vcc
	v_cmp_le_i32_e32 vcc, 9, v52
	v_cndmask_b32_e32 v23, v217, v23, vcc
	v_cmp_le_i32_e32 vcc, 41, v52
	v_cndmask_b32_e32 v39, v217, v39, vcc
	v_cmp_le_i32_e32 vcc, 10, v52
	v_cndmask_b32_e32 v24, v217, v24, vcc
	v_cmp_le_i32_e32 vcc, 42, v52
	v_cndmask_b32_e32 v40, v217, v40, vcc
	v_cmp_le_i32_e32 vcc, 11, v52
	v_cndmask_b32_e32 v25, v217, v25, vcc
	v_cmp_le_i32_e32 vcc, 43, v52
	v_cndmask_b32_e32 v41, v217, v41, vcc
	v_cmp_le_i32_e32 vcc, 16, v52
	v_cndmask_b32_e32 v26, v217, v26, vcc
	v_cmp_le_i32_e32 vcc, 48, v52
	v_cndmask_b32_e32 v42, v217, v42, vcc
	v_cmp_le_i32_e32 vcc, 17, v52
	v_cndmask_b32_e32 v27, v217, v27, vcc
	v_cmp_le_i32_e32 vcc, 49, v52
	v_cndmask_b32_e32 v43, v217, v43, vcc
	v_cmp_le_i32_e32 vcc, 18, v52
	v_cndmask_b32_e32 v28, v217, v28, vcc
	v_cmp_le_i32_e32 vcc, 50, v52
	v_cndmask_b32_e32 v44, v217, v44, vcc
	v_cmp_le_i32_e32 vcc, 19, v52
	v_cndmask_b32_e32 v29, v217, v29, vcc
	v_cmp_le_i32_e32 vcc, 51, v52
	v_cndmask_b32_e32 v45, v217, v45, vcc
	v_cmp_le_i32_e32 vcc, 24, v52
	v_cndmask_b32_e32 v30, v217, v30, vcc
	v_cmp_le_i32_e32 vcc, 56, v52
	v_cndmask_b32_e32 v46, v217, v46, vcc
	v_cmp_le_i32_e32 vcc, 25, v52
	v_cndmask_b32_e32 v31, v217, v31, vcc
	v_cmp_le_i32_e32 vcc, 57, v52
	v_cndmask_b32_e32 v47, v217, v47, vcc
	v_cmp_le_i32_e32 vcc, 26, v52
	v_cndmask_b32_e32 v32, v217, v32, vcc
	v_cmp_le_i32_e32 vcc, 58, v52
	v_cndmask_b32_e32 v48, v217, v48, vcc
	v_cmp_le_i32_e32 vcc, 27, v52
	v_cndmask_b32_e32 v33, v217, v33, vcc
	v_cmp_le_i32_e32 vcc, 59, v52
	v_cndmask_b32_e32 v49, v217, v49, vcc

; #define WAIT_BAR(N) asm volatile("s_waitcnt vmcnt(" #N ") lgkmcnt(0)\n\ts_barrier":::"memory")
;   #define DMA_K(t,slot) glds16(ksrc+(long)(t)*KVBLK*PIN,(unsigned)__builtin_amdgcn_readfirstlane(kdst+(slot)))
; template<int THRL> __device__ __forceinline__ void attn_unit(long rowbase,int qb,int t0,bool WIN,bool NOMAX,const bf16*Qc,const bf16*__restrict__ Kc,const bf16*__restrict__ Vc,bf16*Oc,float s2,float sink2,char*shm,
;     bf16x8 (&qr)[4],bool pref,const bf16*qkvb,int vn,int in_){
;     ...
;   if(!pref){ DMA_K(2,2*SLOTB);
;     WAIT_BAR(3); }
.LBB0_354:
	s_cmp_lg_u32 0, -1
	s_cselect_b32 s38, 0, 0
	s_add_i32 s38, s38, s82
	v_lshl_add_u64 v[18:19], v[194:195], 0, s[0:1]
	s_addk_i32 s38, 0x4000
	s_mov_b32 s39, m0
	s_mov_b32 m0, s38
	s_nop 0
	global_load_lds_dwordx4 v[18:19], off
	s_mov_b32 m0, s39
	s_waitcnt vmcnt(0) lgkmcnt(0)
	s_barrier
	s_cbranch_execz .LBB0_264
	s_branch .LBB0_265
